# v11: prompt attention rewritten by hand: K and V^T key tiles staged once per workgroup in swizzled LDS and shared by the 8 waves (same bf16 MFMA / f32 softmax math); compiler loop keeps sample items
# speedup vs baseline: 1.1588x; 1.0494x over previous
.LBB0_1308:
	s_or_b64 exec, exec, s[8:9]
	v_mov_b32_e32 v0, v174
	s_add_u32 s58, s74, 0x35e65c00
	s_barrier
	s_addc_u32 s59, s75, 0
	v_and_b32_e32 v1, 15, v174
	v_bfe_u32 v2, v174, 4, 2
	v_lshrrev_b32_e32 v3, 6, v174
	v_and_b32_e32 v4, 63, v174
	v_mov_b32_e32 v125, 0xf149f2ca
	v_readfirstlane_b32 s80, v3
	s_lshr_b32 s81, s33, 3
	v_lshrrev_b32_e32 v116, 3, v4
	v_lshrrev_b32_e32 v117, 4, v4
	v_and_b32_e32 v118, 1, v3
	v_lshl_add_u32 v118, v118, 2, v117
	v_and_b32_e32 v119, 7, v4
	v_xor_b32_e32 v119, v119, v118
	v_lshl_add_u32 v5, v3, 3, v116
	v_lshlrev_b32_e32 v5, 7, v5
	v_lshl_add_u32 v5, v119, 4, v5
	v_lshrrev_b32_e32 v6, 5, v4
	v_lshl_add_u32 v6, v3, 1, v6
	v_and_b32_e32 v120, 31, v4
	v_xor_b32_e32 v120, v120, v6
	v_lshlrev_b32_e32 v7, 4, v120
	v_and_b32_e32 v8, 16, v4
	v_xor_b32_e32 v8, 16, v8
	v_lshlrev_b32_e32 v8, 4, v8
	v_lshlrev_b32_e32 v9, 4, v4
	v_lshl_add_u32 v9, v3, 10, v9
	v_lshrrev_b32_e32 v121, 1, v1
	v_xor_b32_e32 v122, v2, v121
	v_lshl_add_u32 v10, v3, 4, v1
	v_lshlrev_b32_e32 v10, 7, v10
	v_xor_b32_e32 v123, 4, v122
	v_lshl_add_u32 v11, v123, 4, v10
	v_lshl_add_u32 v10, v122, 4, v10
	v_and_b32_e32 v12, 1, v2
	v_lshlrev_b32_e32 v12, 3, v12
	v_lshl_add_u32 v12, v1, 9, v12
	v_add_u32_e32 v12, 0x8000, v12
	v_lshrrev_b32_e32 v13, 1, v2
	v_lshl_add_u32 v13, v3, 1, v13
	v_lshlrev_b32_e32 v14, 2, v2
	v_sub_u32_e32 v14, v1, v14
	v_xor_b32_e32 v16, 16, v4
	v_lshlrev_b32_e32 v16, 2, v16
	v_xor_b32_e32 v17, 32, v4
	v_lshlrev_b32_e32 v17, 2, v17
	v_lshl_add_u32 v19, v3, 4, v1
	v_lshlrev_b32_e32 v18, 7, v19
	v_lshl_add_u32 v18, v2, 4, v18
	s_add_u32 s4, s74, 0x35e65c00
	s_addc_u32 s5, s75, 0
	s_add_u32 s6, s74, 0x3bfe5c00
	s_addc_u32 s7, s75, 0
	s_cmpk_ge_u32 s81, 0x600
	s_cselect_b32 s82, 1, 0
	s_mul_i32 s95, s82, 0x600
	s_sub_i32 s95, s81, s95
	s_lshr_b32 s83, s95, 6
	s_and_b32 s95, s95, 63
	s_lshr_b32 s84, s83, 3
	s_lshl_b32 s84, s84, 1
	s_sub_i32 s98, 6, s84
	s_lshr_b32 s85, s95, s98
	s_lshl_b32 s99, 1, s98
	s_add_i32 s99, s99, -1
	s_and_b32 s86, s95, s99
	s_lshr_b32 s87, 0x2000, s84
	s_mul_i32 s95, s82, 24
	s_add_i32 s95, s95, s83
	s_lshl_b32 s95, s95, 13
	s_mul_i32 s99, s85, s87
	s_add_i32 s95, s95, s99
	s_lshl_b32 s95, s95, 7
	s_add_u32 s88, s74, 0x16665c00
	s_addc_u32 s89, s75, 0
	s_add_u32 s88, s88, s95
	s_addc_u32 s89, s89, 0
	s_add_u32 s90, s74, 0x19665c00
	s_addc_u32 s91, s75, 0
	s_add_u32 s90, s90, s95
	s_addc_u32 s91, s91, 0
	s_add_u32 s92, s74, 0x135a5c00
	s_addc_u32 s93, s75, 0
	s_add_u32 s92, s92, s95
	s_addc_u32 s93, s93, 0
	s_lshl_b32 s95, s86, 14
	s_add_u32 s92, s92, s95
	s_addc_u32 s93, s93, 0
	s_cmp_eq_u32 s86, 0
	s_cselect_b32 s94, -1, 0
	s_cselect_b32 s100, 0x4000, 0
	s_add_i32 s95, s95, 0xffffc000
	s_ashr_i32 s99, s95, 31
	s_add_u32 s88, s88, s95
	s_addc_u32 s89, s89, s99
	s_lshl_b32 s95, s86, 8
	s_add_i32 s95, s95, 0xffffff00
	s_ashr_i32 s99, s95, 31
	s_add_u32 s90, s90, s95
	s_addc_u32 s91, s91, s99
	s_sub_i32 s98, 14, s84
	v_lshlrev_b32_e32 v124, s98, v6
	v_and_b32_e32 v126, s94, v8
	v_add3_u32 v124, v124, v7, v126
	s_add_i32 s98, s98, 4
	s_add_i32 s99, s100, 0
	v_add_u32_e32 v126, s99, v5
	global_load_dwordx4 v[128:131], v126, s[88:89]
	s_add_i32 s99, s100, 8192
	v_add_u32_e32 v126, s99, v5
	global_load_dwordx4 v[132:135], v126, s[88:89]
	v_add_u32_e32 v126, 0x4000, v5
	global_load_dwordx4 v[136:139], v126, s[88:89]
	v_add_u32_e32 v126, 0x6000, v5
	global_load_dwordx4 v[140:143], v126, s[88:89]
	global_load_dwordx4 v[144:147], v124, s[90:91]
	s_lshl_b32 s99, 1, s98
	v_add_u32_e32 v126, s99, v124
	global_load_dwordx4 v[148:151], v126, s[90:91]
	s_lshl_b32 s99, 2, s98
	v_add_u32_e32 v126, s99, v124
	global_load_dwordx4 v[152:155], v126, s[90:91]
	s_lshl_b32 s99, 3, s98
	v_add_u32_e32 v126, s99, v124
	global_load_dwordx4 v[156:159], v126, s[90:91]
	global_load_dwordx4 v[160:163], v18, s[92:93]
	global_load_dwordx4 v[164:167], v18, s[92:93] offset:64
.Lpa_loop:
	s_waitcnt vmcnt(0)
	s_barrier
	ds_write_b128 v9, v[128:131]
	ds_write_b128 v9, v[132:135] offset:8192
	ds_write_b128 v9, v[136:139] offset:16384
	ds_write_b128 v9, v[140:143] offset:24576
	ds_write_b128 v9, v[144:147] offset:32768
	ds_write_b128 v9, v[148:151] offset:40960
	ds_write_b128 v9, v[152:155] offset:49152
	ds_write_b128 v9, v[156:159] offset:57344
	v_mov_b32_e32 v178, v160
	v_mov_b32_e32 v179, v161
	v_mov_b32_e32 v180, v162
	v_mov_b32_e32 v181, v163
	v_mov_b32_e32 v182, v164
	v_mov_b32_e32 v183, v165
	v_mov_b32_e32 v184, v166
	v_mov_b32_e32 v185, v167
	s_lshl_b32 s95, s86, 7
	v_add_u32_e32 v168, s95, v19
	v_lshlrev_b32_e32 v168, s84, v168
	s_lshl_b32 s95, s82, 13
	s_add_i32 s95, s95, s85
	v_add_u32_e32 v168, s95, v168
	s_movk_i32 s99, 0x1800
	v_mul_lo_u32 v169, v168, s99
	s_lshl_b32 s95, s83, 8
	v_lshl_add_u32 v126, v2, 4, s95
	v_add_u32_e32 v169, v169, v126
	v_mul_u32_u24_e32 v170, 24, v168
	v_add_lshl_u32 v170, v170, s83, 2
	s_mov_b32 s62, s94
	s_sub_i32 s63, 8, s80
	s_waitcnt lgkmcnt(0)
	s_barrier
	s_addk_i32 s81, 0x100
	s_cmpk_lt_u32 s81, 0xc00
	s_cbranch_scc0 .Lpa_nopf
	s_cmpk_ge_u32 s81, 0x600
	s_cselect_b32 s82, 1, 0
	s_mul_i32 s95, s82, 0x600
	s_sub_i32 s95, s81, s95
	s_lshr_b32 s83, s95, 6
	s_and_b32 s95, s95, 63
	s_lshr_b32 s84, s83, 3
	s_lshl_b32 s84, s84, 1
	s_sub_i32 s98, 6, s84
	s_lshr_b32 s85, s95, s98
	s_lshl_b32 s99, 1, s98
	s_add_i32 s99, s99, -1
	s_and_b32 s86, s95, s99
	s_lshr_b32 s87, 0x2000, s84
	s_mul_i32 s95, s82, 24
	s_add_i32 s95, s95, s83
	s_lshl_b32 s95, s95, 13
	s_mul_i32 s99, s85, s87
	s_add_i32 s95, s95, s99
	s_lshl_b32 s95, s95, 7
	s_add_u32 s88, s74, 0x16665c00
	s_addc_u32 s89, s75, 0
	s_add_u32 s88, s88, s95
	s_addc_u32 s89, s89, 0
	s_add_u32 s90, s74, 0x19665c00
	s_addc_u32 s91, s75, 0
	s_add_u32 s90, s90, s95
	s_addc_u32 s91, s91, 0
	s_add_u32 s92, s74, 0x135a5c00
	s_addc_u32 s93, s75, 0
	s_add_u32 s92, s92, s95
	s_addc_u32 s93, s93, 0
	s_lshl_b32 s95, s86, 14
	s_add_u32 s92, s92, s95
	s_addc_u32 s93, s93, 0
	s_cmp_eq_u32 s86, 0
	s_cselect_b32 s94, -1, 0
	s_cselect_b32 s100, 0x4000, 0
	s_add_i32 s95, s95, 0xffffc000
	s_ashr_i32 s99, s95, 31
	s_add_u32 s88, s88, s95
	s_addc_u32 s89, s89, s99
	s_lshl_b32 s95, s86, 8
	s_add_i32 s95, s95, 0xffffff00
	s_ashr_i32 s99, s95, 31
	s_add_u32 s90, s90, s95
	s_addc_u32 s91, s91, s99
	s_sub_i32 s98, 14, s84
	v_lshlrev_b32_e32 v124, s98, v6
	v_and_b32_e32 v126, s94, v8
	v_add3_u32 v124, v124, v7, v126
	s_add_i32 s98, s98, 4
	s_add_i32 s99, s100, 0
	v_add_u32_e32 v126, s99, v5
	global_load_dwordx4 v[128:131], v126, s[88:89]
	s_add_i32 s99, s100, 8192
	v_add_u32_e32 v126, s99, v5
	global_load_dwordx4 v[132:135], v126, s[88:89]
	v_add_u32_e32 v126, 0x4000, v5
	global_load_dwordx4 v[136:139], v126, s[88:89]
	v_add_u32_e32 v126, 0x6000, v5
	global_load_dwordx4 v[140:143], v126, s[88:89]
	global_load_dwordx4 v[144:147], v124, s[90:91]
	s_lshl_b32 s99, 1, s98
	v_add_u32_e32 v126, s99, v124
	global_load_dwordx4 v[148:151], v126, s[90:91]
	s_lshl_b32 s99, 2, s98
	v_add_u32_e32 v126, s99, v124
	global_load_dwordx4 v[152:155], v126, s[90:91]
	s_lshl_b32 s99, 3, s98
	v_add_u32_e32 v126, s99, v124
	global_load_dwordx4 v[156:159], v126, s[90:91]
	global_load_dwordx4 v[160:163], v18, s[92:93]
	global_load_dwordx4 v[164:167], v18, s[92:93] offset:64
.Lpa_nopf:
	ds_read_b128 v[72:75], v10
	ds_read_b128 v[76:79], v11
	ds_read_b128 v[80:83], v10 offset:2048
	ds_read_b128 v[84:87], v11 offset:2048
	ds_read_b128 v[88:91], v10 offset:4096
	ds_read_b128 v[92:95], v11 offset:4096
	s_waitcnt lgkmcnt(0)
	v_mfma_f32_16x16x32_bf16 v[20:23], v[72:75], v[178:181], 0
	v_mfma_f32_16x16x32_bf16 v[24:27], v[80:83], v[178:181], 0
	v_mfma_f32_16x16x32_bf16 v[28:31], v[88:91], v[178:181], 0
	v_mfma_f32_16x16x32_bf16 v[20:23], v[76:79], v[182:185], v[20:23]
	v_mfma_f32_16x16x32_bf16 v[24:27], v[84:87], v[182:185], v[24:27]
	v_mfma_f32_16x16x32_bf16 v[28:31], v[92:95], v[182:185], v[28:31]
	ds_read_b128 v[72:75], v10 offset:6144
	ds_read_b128 v[76:79], v11 offset:6144
	ds_read_b128 v[80:83], v10 offset:8192
	ds_read_b128 v[84:87], v11 offset:8192
	ds_read_b128 v[88:91], v10 offset:10240
	ds_read_b128 v[92:95], v11 offset:10240
	s_waitcnt lgkmcnt(0)
	v_mfma_f32_16x16x32_bf16 v[32:35], v[72:75], v[178:181], 0
	v_mfma_f32_16x16x32_bf16 v[36:39], v[80:83], v[178:181], 0
	v_mfma_f32_16x16x32_bf16 v[40:43], v[88:91], v[178:181], 0
	v_mfma_f32_16x16x32_bf16 v[32:35], v[76:79], v[182:185], v[32:35]
	v_mfma_f32_16x16x32_bf16 v[36:39], v[84:87], v[182:185], v[36:39]
	v_mfma_f32_16x16x32_bf16 v[40:43], v[92:95], v[182:185], v[40:43]
	ds_read_b128 v[72:75], v10 offset:12288
	ds_read_b128 v[76:79], v11 offset:12288
	ds_read_b128 v[80:83], v10 offset:14336
	ds_read_b128 v[84:87], v11 offset:14336
	ds_read_b128 v[88:91], v10 offset:16384
	ds_read_b128 v[92:95], v11 offset:16384
	s_waitcnt lgkmcnt(0)
	v_mfma_f32_16x16x32_bf16 v[44:47], v[72:75], v[178:181], 0
	v_mfma_f32_16x16x32_bf16 v[48:51], v[80:83], v[178:181], 0
	v_mfma_f32_16x16x32_bf16 v[52:55], v[88:91], v[178:181], 0
	v_mfma_f32_16x16x32_bf16 v[44:47], v[76:79], v[182:185], v[44:47]
	v_mfma_f32_16x16x32_bf16 v[48:51], v[84:87], v[182:185], v[48:51]
	v_mfma_f32_16x16x32_bf16 v[52:55], v[92:95], v[182:185], v[52:55]
	v_mov_b32_e32 v56, 0
	v_mov_b32_e32 v57, 0
	v_mov_b32_e32 v58, 0
	v_mov_b32_e32 v59, 0
	v_mov_b32_e32 v60, 0
	v_mov_b32_e32 v61, 0
	v_mov_b32_e32 v62, 0
	v_mov_b32_e32 v63, 0
	v_mov_b32_e32 v64, 0
	v_mov_b32_e32 v65, 0
	v_mov_b32_e32 v66, 0
	v_mov_b32_e32 v67, 0
	v_mov_b32_e32 v68, 0
	v_mov_b32_e32 v69, 0
	v_mov_b32_e32 v70, 0
	v_mov_b32_e32 v71, 0
	s_nop 7
	s_nop 7
	v_cmp_ge_i32_e64 s[46:47], 0, v14
	v_cmp_ge_i32_e64 s[98:99], 1, v14
	v_cmp_ge_i32_e64 s[100:101], 2, v14
	v_cmp_ge_i32_e64 vcc, 3, v14
	s_nop 1
	v_cndmask_b32_e64 v20, v125, v20, s[46:47]
	v_cndmask_b32_e64 v21, v125, v21, s[98:99]
	v_cndmask_b32_e64 v22, v125, v22, s[100:101]
	v_cndmask_b32_e32 v23, v125, v23, vcc
	v_cmp_le_i32_e64 s[46:47], 0, v14
	v_cmp_le_i32_e64 s[98:99], 1, v14
	v_cmp_le_i32_e64 s[100:101], 2, v14
	v_cmp_le_i32_e64 vcc, 3, v14
	s_nop 1
	v_cndmask_b32_e64 v52, v125, v52, s[46:47]
	v_cndmask_b32_e64 v53, v125, v53, s[98:99]
	v_cndmask_b32_e64 v54, v125, v54, s[100:101]
	v_cndmask_b32_e32 v55, v125, v55, vcc
	s_cmp_eq_u32 s62, 0
	s_cbranch_scc1 .Lpa_nomask
	s_cmp_gt_u32 s63, 0
	s_cbranch_scc0 .Lpa_nomask
	v_mov_b32_e32 v20, v125
	v_mov_b32_e32 v21, v125
	v_mov_b32_e32 v22, v125
	v_mov_b32_e32 v23, v125
	s_cmp_gt_u32 s63, 1
	s_cbranch_scc0 .Lpa_nomask
	v_mov_b32_e32 v24, v125
	v_mov_b32_e32 v25, v125
	v_mov_b32_e32 v26, v125
	v_mov_b32_e32 v27, v125
	s_cmp_gt_u32 s63, 2
	s_cbranch_scc0 .Lpa_nomask
	v_mov_b32_e32 v28, v125
	v_mov_b32_e32 v29, v125
	v_mov_b32_e32 v30, v125
	v_mov_b32_e32 v31, v125
	s_cmp_gt_u32 s63, 3
	s_cbranch_scc0 .Lpa_nomask
	v_mov_b32_e32 v32, v125
	v_mov_b32_e32 v33, v125
	v_mov_b32_e32 v34, v125
	v_mov_b32_e32 v35, v125
	s_cmp_gt_u32 s63, 4
	s_cbranch_scc0 .Lpa_nomask
	v_mov_b32_e32 v36, v125
	v_mov_b32_e32 v37, v125
	v_mov_b32_e32 v38, v125
	v_mov_b32_e32 v39, v125
	s_cmp_gt_u32 s63, 5
	s_cbranch_scc0 .Lpa_nomask
	v_mov_b32_e32 v40, v125
	v_mov_b32_e32 v41, v125
	v_mov_b32_e32 v42, v125
	v_mov_b32_e32 v43, v125
	s_cmp_gt_u32 s63, 6
	s_cbranch_scc0 .Lpa_nomask
	v_mov_b32_e32 v44, v125
	v_mov_b32_e32 v45, v125
	v_mov_b32_e32 v46, v125
	v_mov_b32_e32 v47, v125
	s_cmp_gt_u32 s63, 7
	s_cbranch_scc0 .Lpa_nomask
	v_mov_b32_e32 v48, v125
	v_mov_b32_e32 v49, v125
	v_mov_b32_e32 v50, v125
	v_mov_b32_e32 v51, v125
.Lpa_nomask:
	v_max3_f32 v187, v20, v21, v22
	v_max3_f32 v187, v187, v23, v24
	v_max3_f32 v187, v187, v25, v26
	v_max3_f32 v187, v187, v27, v28
	v_max3_f32 v187, v187, v29, v30
	v_max3_f32 v187, v187, v31, v32
	v_max3_f32 v187, v187, v33, v34
	v_max3_f32 v187, v187, v35, v36
	v_max3_f32 v187, v187, v37, v38
	v_max3_f32 v187, v187, v39, v40
	v_max3_f32 v187, v187, v41, v42
	v_max3_f32 v187, v187, v43, v44
	v_max3_f32 v187, v187, v45, v46
	v_max3_f32 v187, v187, v47, v48
	v_max3_f32 v187, v187, v49, v50
	v_max3_f32 v187, v187, v51, v52
	v_max3_f32 v187, v187, v53, v54
	v_max_f32_e32 v187, v187, v55
	ds_bpermute_b32 v126, v16, v187
	s_waitcnt lgkmcnt(0)
	v_max_f32_e32 v187, v187, v126
	ds_bpermute_b32 v126, v17, v187
	s_waitcnt lgkmcnt(0)
	v_max_f32_e32 v187, v187, v126
	v_mov_b32_e32 v188, 0
	v_sub_f32_e32 v20, v20, v187
	v_sub_f32_e32 v21, v21, v187
	v_sub_f32_e32 v22, v22, v187
	v_sub_f32_e32 v23, v23, v187
	v_mul_f32_e32 v20, 0x3fb8aa3b, v20
	v_mul_f32_e32 v21, 0x3fb8aa3b, v21
	v_mul_f32_e32 v22, 0x3fb8aa3b, v22
	v_mul_f32_e32 v23, 0x3fb8aa3b, v23
	v_exp_f32_e32 v20, v20
	v_exp_f32_e32 v21, v21
	v_exp_f32_e32 v22, v22
	v_exp_f32_e32 v23, v23
	s_nop 0
	v_add_f32_e32 v188, v188, v20
	v_add_f32_e32 v188, v188, v21
	v_add_f32_e32 v188, v188, v22
	v_add_f32_e32 v188, v188, v23
	v_sub_f32_e32 v24, v24, v187
	v_sub_f32_e32 v25, v25, v187
	v_sub_f32_e32 v26, v26, v187
	v_sub_f32_e32 v27, v27, v187
	v_mul_f32_e32 v24, 0x3fb8aa3b, v24
	v_mul_f32_e32 v25, 0x3fb8aa3b, v25
	v_mul_f32_e32 v26, 0x3fb8aa3b, v26
	v_mul_f32_e32 v27, 0x3fb8aa3b, v27
	v_exp_f32_e32 v24, v24
	v_exp_f32_e32 v25, v25
	v_exp_f32_e32 v26, v26
	v_exp_f32_e32 v27, v27
	s_nop 0
	v_add_f32_e32 v188, v188, v24
	v_add_f32_e32 v188, v188, v25
	v_add_f32_e32 v188, v188, v26
	v_add_f32_e32 v188, v188, v27
	v_sub_f32_e32 v28, v28, v187
	v_sub_f32_e32 v29, v29, v187
	v_sub_f32_e32 v30, v30, v187
	v_sub_f32_e32 v31, v31, v187
	v_mul_f32_e32 v28, 0x3fb8aa3b, v28
	v_mul_f32_e32 v29, 0x3fb8aa3b, v29
	v_mul_f32_e32 v30, 0x3fb8aa3b, v30
	v_mul_f32_e32 v31, 0x3fb8aa3b, v31
	v_exp_f32_e32 v28, v28
	v_exp_f32_e32 v29, v29
	v_exp_f32_e32 v30, v30
	v_exp_f32_e32 v31, v31
	s_nop 0
	v_add_f32_e32 v188, v188, v28
	v_add_f32_e32 v188, v188, v29
	v_add_f32_e32 v188, v188, v30
	v_add_f32_e32 v188, v188, v31
	v_sub_f32_e32 v32, v32, v187
	v_sub_f32_e32 v33, v33, v187
	v_sub_f32_e32 v34, v34, v187
	v_sub_f32_e32 v35, v35, v187
	v_mul_f32_e32 v32, 0x3fb8aa3b, v32
	v_mul_f32_e32 v33, 0x3fb8aa3b, v33
	v_mul_f32_e32 v34, 0x3fb8aa3b, v34
	v_mul_f32_e32 v35, 0x3fb8aa3b, v35
	v_exp_f32_e32 v32, v32
	v_exp_f32_e32 v33, v33
	v_exp_f32_e32 v34, v34
	v_exp_f32_e32 v35, v35
	s_nop 0
	v_add_f32_e32 v188, v188, v32
	v_add_f32_e32 v188, v188, v33
	v_add_f32_e32 v188, v188, v34
	v_add_f32_e32 v188, v188, v35
	v_sub_f32_e32 v36, v36, v187
	v_sub_f32_e32 v37, v37, v187
	v_sub_f32_e32 v38, v38, v187
	v_sub_f32_e32 v39, v39, v187
	v_mul_f32_e32 v36, 0x3fb8aa3b, v36
	v_mul_f32_e32 v37, 0x3fb8aa3b, v37
	v_mul_f32_e32 v38, 0x3fb8aa3b, v38
	v_mul_f32_e32 v39, 0x3fb8aa3b, v39
	v_exp_f32_e32 v36, v36
	v_exp_f32_e32 v37, v37
	v_exp_f32_e32 v38, v38
	v_exp_f32_e32 v39, v39
	s_nop 0
	v_add_f32_e32 v188, v188, v36
	v_add_f32_e32 v188, v188, v37
	v_add_f32_e32 v188, v188, v38
	v_add_f32_e32 v188, v188, v39
	v_sub_f32_e32 v40, v40, v187
	v_sub_f32_e32 v41, v41, v187
	v_sub_f32_e32 v42, v42, v187
	v_sub_f32_e32 v43, v43, v187
	v_mul_f32_e32 v40, 0x3fb8aa3b, v40
	v_mul_f32_e32 v41, 0x3fb8aa3b, v41
	v_mul_f32_e32 v42, 0x3fb8aa3b, v42
	v_mul_f32_e32 v43, 0x3fb8aa3b, v43
	v_exp_f32_e32 v40, v40
	v_exp_f32_e32 v41, v41
	v_exp_f32_e32 v42, v42
	v_exp_f32_e32 v43, v43
	s_nop 0
	v_add_f32_e32 v188, v188, v40
	v_add_f32_e32 v188, v188, v41
	v_add_f32_e32 v188, v188, v42
	v_add_f32_e32 v188, v188, v43
	v_sub_f32_e32 v44, v44, v187
	v_sub_f32_e32 v45, v45, v187
	v_sub_f32_e32 v46, v46, v187
	v_sub_f32_e32 v47, v47, v187
	v_mul_f32_e32 v44, 0x3fb8aa3b, v44
	v_mul_f32_e32 v45, 0x3fb8aa3b, v45
	v_mul_f32_e32 v46, 0x3fb8aa3b, v46
	v_mul_f32_e32 v47, 0x3fb8aa3b, v47
	v_exp_f32_e32 v44, v44
	v_exp_f32_e32 v45, v45
	v_exp_f32_e32 v46, v46
	v_exp_f32_e32 v47, v47
	s_nop 0
	v_add_f32_e32 v188, v188, v44
	v_add_f32_e32 v188, v188, v45
	v_add_f32_e32 v188, v188, v46
	v_add_f32_e32 v188, v188, v47
	v_sub_f32_e32 v48, v48, v187
	v_sub_f32_e32 v49, v49, v187
	v_sub_f32_e32 v50, v50, v187
	v_sub_f32_e32 v51, v51, v187
	v_mul_f32_e32 v48, 0x3fb8aa3b, v48
	v_mul_f32_e32 v49, 0x3fb8aa3b, v49
	v_mul_f32_e32 v50, 0x3fb8aa3b, v50
	v_mul_f32_e32 v51, 0x3fb8aa3b, v51
	v_exp_f32_e32 v48, v48
	v_exp_f32_e32 v49, v49
	v_exp_f32_e32 v50, v50
	v_exp_f32_e32 v51, v51
	s_nop 0
	v_add_f32_e32 v188, v188, v48
	v_add_f32_e32 v188, v188, v49
	v_add_f32_e32 v188, v188, v50
	v_add_f32_e32 v188, v188, v51
	v_sub_f32_e32 v52, v52, v187
	v_sub_f32_e32 v53, v53, v187
	v_sub_f32_e32 v54, v54, v187
	v_sub_f32_e32 v55, v55, v187
	v_mul_f32_e32 v52, 0x3fb8aa3b, v52
	v_mul_f32_e32 v53, 0x3fb8aa3b, v53
	v_mul_f32_e32 v54, 0x3fb8aa3b, v54
	v_mul_f32_e32 v55, 0x3fb8aa3b, v55
	v_exp_f32_e32 v52, v52
	v_exp_f32_e32 v53, v53
	v_exp_f32_e32 v54, v54
	v_exp_f32_e32 v55, v55
	s_nop 0
	v_add_f32_e32 v188, v188, v52
	v_add_f32_e32 v188, v188, v53
	v_add_f32_e32 v188, v188, v54
	v_add_f32_e32 v188, v188, v55
	ds_bpermute_b32 v126, v16, v188
	s_waitcnt lgkmcnt(0)
	v_add_f32_e32 v188, v188, v126
	ds_bpermute_b32 v126, v17, v188
	s_waitcnt lgkmcnt(0)
	v_add_f32_e32 v188, v188, v126
	v_cvt_pk_bf16_f32 v112, v20, v21
	v_cvt_pk_bf16_f32 v113, v22, v23
	v_cvt_pk_bf16_f32 v114, v24, v25
	v_cvt_pk_bf16_f32 v115, v26, v27
	v_add_u32_e32 v126, 0, v13
	v_xor_b32_e32 v126, v126, v1
	v_lshl_add_u32 v126, v126, 4, v12
	ds_read_b64 v[96:97], v126
	ds_read_b64 v[100:101], v126 offset:8192
	ds_read_b64 v[104:105], v126 offset:16384
	ds_read_b64 v[108:109], v126 offset:24576
	v_add_u32_e32 v126, 2, v13
	v_xor_b32_e32 v126, v126, v1
	v_lshl_add_u32 v126, v126, 4, v12
	ds_read_b64 v[98:99], v126
	ds_read_b64 v[102:103], v126 offset:8192
	ds_read_b64 v[106:107], v126 offset:16384
	ds_read_b64 v[110:111], v126 offset:24576
	s_waitcnt lgkmcnt(0)
	v_mfma_f32_16x16x32_bf16 v[56:59], v[96:99], v[112:115], v[56:59]
	v_mfma_f32_16x16x32_bf16 v[60:63], v[100:103], v[112:115], v[60:63]
	v_mfma_f32_16x16x32_bf16 v[64:67], v[104:107], v[112:115], v[64:67]
	v_mfma_f32_16x16x32_bf16 v[68:71], v[108:111], v[112:115], v[68:71]
	v_cvt_pk_bf16_f32 v112, v28, v29
	v_cvt_pk_bf16_f32 v113, v30, v31
	v_cvt_pk_bf16_f32 v114, v32, v33
	v_cvt_pk_bf16_f32 v115, v34, v35
	v_add_u32_e32 v126, 4, v13
	v_xor_b32_e32 v126, v126, v1
	v_lshl_add_u32 v126, v126, 4, v12
	ds_read_b64 v[96:97], v126
	ds_read_b64 v[100:101], v126 offset:8192
	ds_read_b64 v[104:105], v126 offset:16384
	ds_read_b64 v[108:109], v126 offset:24576
	v_add_u32_e32 v126, 6, v13
	v_xor_b32_e32 v126, v126, v1
	v_lshl_add_u32 v126, v126, 4, v12
	ds_read_b64 v[98:99], v126
	ds_read_b64 v[102:103], v126 offset:8192
	ds_read_b64 v[106:107], v126 offset:16384
	ds_read_b64 v[110:111], v126 offset:24576
	s_waitcnt lgkmcnt(0)
	v_mfma_f32_16x16x32_bf16 v[56:59], v[96:99], v[112:115], v[56:59]
	v_mfma_f32_16x16x32_bf16 v[60:63], v[100:103], v[112:115], v[60:63]
	v_mfma_f32_16x16x32_bf16 v[64:67], v[104:107], v[112:115], v[64:67]
	v_mfma_f32_16x16x32_bf16 v[68:71], v[108:111], v[112:115], v[68:71]
	v_cvt_pk_bf16_f32 v112, v36, v37
	v_cvt_pk_bf16_f32 v113, v38, v39
	v_cvt_pk_bf16_f32 v114, v40, v41
	v_cvt_pk_bf16_f32 v115, v42, v43
	v_add_u32_e32 v126, 8, v13
	v_xor_b32_e32 v126, v126, v1
	v_lshl_add_u32 v126, v126, 4, v12
	ds_read_b64 v[96:97], v126
	ds_read_b64 v[100:101], v126 offset:8192
	ds_read_b64 v[104:105], v126 offset:16384
	ds_read_b64 v[108:109], v126 offset:24576
	v_add_u32_e32 v126, 10, v13
	v_xor_b32_e32 v126, v126, v1
	v_lshl_add_u32 v126, v126, 4, v12
	ds_read_b64 v[98:99], v126
	ds_read_b64 v[102:103], v126 offset:8192
	ds_read_b64 v[106:107], v126 offset:16384
	ds_read_b64 v[110:111], v126 offset:24576
	s_waitcnt lgkmcnt(0)
	v_mfma_f32_16x16x32_bf16 v[56:59], v[96:99], v[112:115], v[56:59]
	v_mfma_f32_16x16x32_bf16 v[60:63], v[100:103], v[112:115], v[60:63]
	v_mfma_f32_16x16x32_bf16 v[64:67], v[104:107], v[112:115], v[64:67]
	v_mfma_f32_16x16x32_bf16 v[68:71], v[108:111], v[112:115], v[68:71]
	v_cvt_pk_bf16_f32 v112, v44, v45
	v_cvt_pk_bf16_f32 v113, v46, v47
	v_cvt_pk_bf16_f32 v114, v48, v49
	v_cvt_pk_bf16_f32 v115, v50, v51
	v_add_u32_e32 v126, 12, v13
	v_xor_b32_e32 v126, v126, v1
	v_lshl_add_u32 v126, v126, 4, v12
	ds_read_b64 v[96:97], v126
	ds_read_b64 v[100:101], v126 offset:8192
	ds_read_b64 v[104:105], v126 offset:16384
	ds_read_b64 v[108:109], v126 offset:24576
	v_add_u32_e32 v126, 14, v13
	v_xor_b32_e32 v126, v126, v1
	v_lshl_add_u32 v126, v126, 4, v12
	ds_read_b64 v[98:99], v126
	ds_read_b64 v[102:103], v126 offset:8192
	ds_read_b64 v[106:107], v126 offset:16384
	ds_read_b64 v[110:111], v126 offset:24576
	s_waitcnt lgkmcnt(0)
	v_mfma_f32_16x16x32_bf16 v[56:59], v[96:99], v[112:115], v[56:59]
	v_mfma_f32_16x16x32_bf16 v[60:63], v[100:103], v[112:115], v[60:63]
	v_mfma_f32_16x16x32_bf16 v[64:67], v[104:107], v[112:115], v[64:67]
	v_mfma_f32_16x16x32_bf16 v[68:71], v[108:111], v[112:115], v[68:71]
	v_cvt_pk_bf16_f32 v112, v52, v53
	v_cvt_pk_bf16_f32 v113, v54, v55
	v_mov_b32_e32 v114, 0
	v_mov_b32_e32 v115, 0
	v_add_u32_e32 v126, 16, v13
	v_xor_b32_e32 v126, v126, v1
	v_lshl_add_u32 v126, v126, 4, v12
	ds_read_b64 v[96:97], v126
	ds_read_b64 v[100:101], v126 offset:8192
	ds_read_b64 v[104:105], v126 offset:16384
	ds_read_b64 v[108:109], v126 offset:24576
	v_add_u32_e32 v126, 16, v13
	v_xor_b32_e32 v126, v126, v1
	v_lshl_add_u32 v126, v126, 4, v12
	ds_read_b64 v[98:99], v126
	ds_read_b64 v[102:103], v126 offset:8192
	ds_read_b64 v[106:107], v126 offset:16384
	ds_read_b64 v[110:111], v126 offset:24576
	s_waitcnt lgkmcnt(0)
	v_mfma_f32_16x16x32_bf16 v[56:59], v[96:99], v[112:115], v[56:59]
	v_mfma_f32_16x16x32_bf16 v[60:63], v[100:103], v[112:115], v[60:63]
	v_mfma_f32_16x16x32_bf16 v[64:67], v[104:107], v[112:115], v[64:67]
	v_mfma_f32_16x16x32_bf16 v[68:71], v[108:111], v[112:115], v[68:71]
	s_nop 7
	s_nop 7
	v_div_scale_f32 v116, s[46:47], v188, v188, 1.0
	v_rcp_f32_e32 v117, v116
	v_div_scale_f32 v118, vcc, 1.0, v188, 1.0
	v_fma_f32 v119, -v116, v117, 1.0
	v_fmac_f32_e32 v117, v119, v117
	v_mul_f32_e32 v119, v118, v117
	v_fma_f32 v120, -v116, v119, v118
	v_fmac_f32_e32 v119, v120, v117
	v_fma_f32 v116, -v116, v119, v118
	v_div_fmas_f32 v116, v116, v117, v119
	v_div_fixup_f32 v117, v116, v188, 1.0
	v_mul_f32_e32 v56, v117, v56
	v_mul_f32_e32 v57, v117, v57
	v_mul_f32_e32 v58, v117, v58
	v_mul_f32_e32 v59, v117, v59
	v_mul_f32_e32 v60, v117, v60
	v_mul_f32_e32 v61, v117, v61
	v_mul_f32_e32 v62, v117, v62
	v_mul_f32_e32 v63, v117, v63
	v_mul_f32_e32 v64, v117, v64
	v_mul_f32_e32 v65, v117, v65
	v_mul_f32_e32 v66, v117, v66
	v_mul_f32_e32 v67, v117, v67
	v_mul_f32_e32 v68, v117, v68
	v_mul_f32_e32 v69, v117, v69
	v_mul_f32_e32 v70, v117, v70
	v_mul_f32_e32 v71, v117, v71
	global_store_dwordx4 v169, v[56:59], s[4:5]
	global_store_dwordx4 v169, v[60:63], s[4:5] offset:64
	global_store_dwordx4 v169, v[64:67], s[4:5] offset:128
	global_store_dwordx4 v169, v[68:71], s[4:5] offset:192
	s_mov_b32 s46, 0x800000
	s_mov_b32 s47, 0x3f317217
	v_cmp_gt_f32_e32 vcc, s46, v188
	s_nop 1
	v_cndmask_b32_e64 v116, 0, 32, vcc
	v_ldexp_f32 v116, v188, v116
	v_log_f32_e32 v116, v116
	v_mov_b32_e32 v118, 0x41b17218
	v_cndmask_b32_e32 v117, 0, v118, vcc
	v_mul_f32_e32 v118, 0x3f317217, v116
	v_fma_f32 v118, v116, s47, -v118
	v_fmac_f32_e32 v118, 0x3377d1cf, v116
	v_fmac_f32_e32 v118, 0x3f317217, v116
	s_mov_b32 s46, 0x7f800000
	v_cmp_lt_f32_e64 vcc, |v116|, s46
	s_nop 1
	v_cndmask_b32_e32 v116, v116, v118, vcc
	v_sub_f32_e32 v116, v116, v117
	v_add_f32_e32 v116, v187, v116
	v_cmp_eq_u32_e64 s[46:47], 0, v2
	s_nop 1
	s_and_saveexec_b64 s[98:99], s[46:47]
	global_store_dword v170, v116, s[6:7]
	s_mov_b64 exec, s[98:99]
	s_cmpk_lt_u32 s81, 0xc00
	s_cbranch_scc1 .Lpa_loop
	v_ashrrev_i32_e32 v1, 6, v0
	s_waitcnt vmcnt(5)
	v_add_u32_e32 v19, s33, v1
	v_add_u32_e32 v19, 0x6000, v19
	s_add_u32 s64, s74, 0x3bfe5c00
	s_movk_i32 s4, 0x6d00
	s_addc_u32 s65, s75, 0
	v_cmp_gt_i32_e32 vcc, s4, v19
	s_and_saveexec_b64 s[66:67], vcc
	s_cbranch_execz .LBB0_1340
	v_mbcnt_hi_u32_b32 v4, -1, v175
	v_and_b32_e32 v6, 64, v4
	v_bfe_u32 v1, v0, 4, 2
	v_xor_b32_e32 v5, 16, v4
	v_add_u32_e32 v6, 64, v6
	v_lshlrev_b32_e32 v18, 2, v1
	v_cmp_lt_i32_e32 vcc, v5, v6
	v_and_b32_e32 v22, 15, v0
	v_lshlrev_b32_e32 v2, 3, v1
	v_cndmask_b32_e32 v5, v4, v5, vcc
	v_cmp_eq_u32_e64 s[8:9], 0, v1
	v_or_b32_e32 v1, 1, v18
	v_or_b32_e32 v3, 0x80, v22
	v_lshlrev_b32_e32 v23, 2, v5
	v_xor_b32_e32 v5, 32, v4
	v_cmp_ge_u32_e64 s[12:13], v1, v22
	v_or_b32_e32 v1, 0x81, v18
	v_cmp_lt_i32_e32 vcc, v5, v6
	v_cmp_gt_u32_e64 s[20:21], v1, v3
	v_or_b32_e32 v1, 0x82, v18
	v_cndmask_b32_e32 v4, v4, v5, vcc
	v_or_b32_e32 v25, 2, v18
	v_or_b32_e32 v26, 3, v18
	v_cmp_gt_u32_e64 s[22:23], v1, v3
	v_or_b32_e32 v1, 0x83, v18
	v_mov_b32_e32 v17, 0
	v_lshlrev_b32_e32 v24, 2, v4
	v_cmp_ge_u32_e64 s[10:11], v18, v22
	v_cmp_ge_u32_e64 s[14:15], v25, v22
	v_cmp_ge_u32_e64 s[16:17], v26, v22
	v_or_b32_e32 v27, 16, v18
	v_or_b32_e32 v28, 17, v18
	v_or_b32_e32 v29, 18, v18
	s_waitcnt vmcnt(0)
	v_or_b32_e32 v30, 19, v18
	v_or_b32_e32 v31, 32, v18
	v_or_b32_e32 v32, 33, v18
	v_or_b32_e32 v33, 34, v18
	v_or_b32_e32 v34, 35, v18
	v_or_b32_e32 v35, 48, v18
	v_or_b32_e32 v36, 49, v18
	v_or_b32_e32 v37, 50, v18
	v_or_b32_e32 v38, 51, v18
	v_or_b32_e32 v39, 64, v18
	v_or_b32_e32 v40, 0x41, v18
	v_or_b32_e32 v41, 0x42, v18
	v_or_b32_e32 v42, 0x43, v18
	v_or_b32_e32 v43, 0x50, v18
	v_or_b32_e32 v44, 0x51, v18
	v_or_b32_e32 v45, 0x52, v18
	v_or_b32_e32 v46, 0x53, v18
	s_movk_i32 s4, 0x60
	v_or_b32_e32 v47, 0x60, v18
	v_or_b32_e32 v48, 0x61, v18
	v_or_b32_e32 v49, 0x62, v18
	v_or_b32_e32 v50, 0x63, v18
	v_or_b32_e32 v51, 0x70, v18
	v_or_b32_e32 v52, 0x71, v18
	v_or_b32_e32 v53, 0x72, v18
	v_or_b32_e32 v54, 0x73, v18
	v_cmp_gt_u32_e64 s[18:19], v18, v22
	v_cmp_gt_u32_e64 s[24:25], v1, v3
	v_or_b32_e32 v55, 0xffffff90, v22
	v_or_b32_e32 v56, 0xffffffb0, v22
	v_or_b32_e32 v57, 0xffffffd0, v22
	v_or_b32_e32 v58, -16, v0
	s_mov_b64 s[68:69], 0
	s_movk_i32 s5, 0x6000
	s_movk_i32 s6, 0x5fff
	s_mov_b32 s7, 0x2aaaaaab
	s_movk_i32 s46, 0x1ff
	s_movk_i32 s47, 0x200
	s_mov_b32 s62, 0x44000
	s_movk_i32 s63, 0x800
	s_movk_i32 s77, 0x2000
	v_lshlrev_b32_e32 v16, 1, v2
	s_movk_i32 s80, 0x6f
	s_movk_i32 s81, 0x4f
	s_mov_b32 s82, 0xff61b1e6
	s_movk_i32 s83, 0xffef
	s_movk_i32 s84, 0x3800
	s_movk_i32 s85, 0x1800
	s_mov_b32 s86, 0x800000
	s_mov_b32 s87, 0x3f317217
	s_mov_b32 s88, 0x7f800000
	s_movk_i32 s89, 0x6cff
	v_mov_b32_e32 v59, 0xf149f2ca
	v_mov_b32_e32 v60, 0x41b17218
	s_branch .LBB0_1311
